# control-word zeroing at kernel start spread grid-stride over all workgroups (was workgroup 0 alone, 32 serial iterations before the grid sync) + every wave drains its stores before the sync; on top of
# baseline (speedup 1.0000x reference)
; #define GAS __attribute__((address_space(1)))
; __global__ void __launch_bounds__(NWAVES * 64, 2) hybrid_fwd(const Args A) {
;     ...
;     if (hi - lo > 1) {
;         if (blockIdx.x == 0) { GAS v4u* z = (GAS v4u*)(F.ws + WS_CTL); for (int i = F.tid; i < (int)(CTL_ZERO_BYTES / 16); i += NWAVES * 64) if (i < (int)(WS_PRM / 16) || i >= (int)((CW_SEAM * 4) / 16)) z[i] = (v4u){0u, 0u, 0u, 0u}; }
;         grid.sync();
.Lprs_init_done:
	s_mov_b64 exec, s[0:1]
	s_add_u32 s0, s86, 0x4000
	s_addc_u32 s1, s87, 0
	v_writelane_b32 v254, s0, 6
	s_mov_b32 s5, 0
	s_waitcnt lgkmcnt(0)
	v_writelane_b32 v254, s1, 7
	s_load_dwordx2 s[0:1], s[72:73], 0x108
	s_barrier
	s_waitcnt lgkmcnt(0)
	s_sub_i32 s4, s1, s0
	s_cmp_gt_i32 s4, 1
	s_cselect_b64 s[0:1], -1, 0
	s_cmp_lt_i32 s4, 2
	s_mov_b32 s4, 0
	v_writelane_b32 v254, s4, 8
	s_cbranch_scc1 .LBB0_26
	s_lshl_b32 s4, s82, 9
	v_add_u32_e32 v8, s4, v210
	s_lshl_b32 s12, s77, 9
	v_mov_b32_e32 v2, 0
	v_mov_b32_e32 v3, v2
	v_mov_b32_e32 v4, v2
	v_mov_b32_e32 v5, v2
	s_mov_b64 s[4:5], exec
.Lcz_loop:
	v_cmp_gt_u32_e32 vcc, 0x4000, v8
	s_and_b64 exec, exec, vcc
	s_cbranch_execz .Lcz_done
	v_add_u32_e32 v9, 0xfffff000, v8
	v_cmp_le_u32_e32 vcc, 0x1000, v9
	s_and_saveexec_b64 s[10:11], vcc
	s_cbranch_execz .Lcz_skip
	v_lshlrev_b32_e32 v6, 4, v8
	v_mov_b32_e32 v7, 0
	v_lshl_add_u64 v[6:7], s[86:87], 0, v[6:7]
	global_store_dwordx4 v[6:7], v[2:5], off
.Lcz_skip:
	s_or_b64 exec, exec, s[10:11]
	v_add_u32_e32 v8, s12, v8
	s_branch .Lcz_loop
.Lcz_done:
	s_mov_b64 exec, s[4:5]
	v_lshrrev_b32_e32 v2, 20, v0
	v_lshrrev_b32_e32 v0, 10, v0
	v_or_b32_e32 v0, v0, v2
	s_movk_i32 s4, 0x3ff
	v_and_or_b32 v0, v0, s4, v1
	v_cmp_eq_u32_e32 vcc, 0, v0
	s_waitcnt vmcnt(0)
	s_barrier
	s_and_saveexec_b64 s[4:5], vcc
	s_cbranch_execz .LBB0_20
	buffer_wbl2 sc1
	s_waitcnt vmcnt(0)
	s_load_dwordx2 s[2:3], s[2:3], 0x58
	v_mov_b32_e32 v2, 0
	s_mov_b64 s[6:7], exec
	v_mbcnt_lo_u32_b32 v1, s6, 0
	v_mbcnt_hi_u32_b32 v1, s7, v1
	s_waitcnt lgkmcnt(0)
	global_load_dword v0, v2, s[2:3] offset:40
	v_cmp_eq_u32_e32 vcc, 0, v1
	s_and_saveexec_b64 s[8:9], vcc
	s_cbranch_execz .LBB0_13
	s_bcnt1_i32_b64 s6, s[6:7]
	v_mov_b32_e32 v3, s6
	global_atomic_add v3, v2, v3, s[2:3] offset:32 sc0
